# EP_U epilogue: silu(a*rs)*(b*rs) regrouped as a*b*rcp((1+e)*q) with q = the rsqrt argument (1/rs^2) and e = exp2(a*(rs*-log2e)); two fewer packed multiplies per output pair, all f32
# speedup vs baseline: 1.0084x; 1.0084x over previous
.LBB0_711:
	s_lshl_b32 s25, s24, 11
	s_and_b32 s25, s25, 0x800
	v_add_u32_e32 v80, s25, v166
	ds_read2_b64 v[140:143], v80 offset1:16
	ds_read2_b64 v[136:139], v80 offset0:32 offset1:48
	ds_read2_b64 v[112:115], v80 offset0:128 offset1:144
	ds_read2_b64 v[80:83], v80 offset0:160 offset1:176
	s_and_b64 s[8:9], s[0:1], s[8:9]
	s_add_u32 s34, s20, 0xc400000
	s_addc_u32 s35, s21, 0
	s_movk_i32 s82, 0xb00
	v_lshl_add_u32 v169, s17, 8, v158
	v_lshl_or_b32 v156, s3, 7, v167
	v_mov_b32_e32 v157, 0
	v_mad_u64_u32 v[156:157], s[42:43], v169, s82, v[156:157]
	s_mov_b32 s82, 0xbfb8aa3b
	s_mov_b32 s38, 1.0
	s_mov_b32 s30, 0x6e000
	s_mov_b32 s31, 0
	v_lshl_add_u64 v[156:157], v[156:157], 1, s[34:35]
	s_mov_b32 s20, 0x16000
	s_mov_b32 s21, 0
	s_waitcnt lgkmcnt(0)
	v_ffbh_u32_e32 v186, v141
	v_ffbh_u32_e32 v187, v143
	v_ffbh_u32_e32 v188, v137
	v_ffbh_u32_e32 v189, v139
	v_ffbh_u32_e32 v190, v113
	v_ffbh_u32_e32 v191, v115
	v_ffbh_u32_e32 v192, v81
	v_ffbh_u32_e32 v193, v83
	v_min_u32_e32 v186, 32, v186
	v_min_u32_e32 v187, 32, v187
	v_min_u32_e32 v188, 32, v188
	v_min_u32_e32 v189, 32, v189
	v_min_u32_e32 v190, 32, v190
	v_min_u32_e32 v191, 32, v191
	v_min_u32_e32 v192, 32, v192
	v_min_u32_e32 v193, 32, v193
	v_lshlrev_b64 v[140:141], v186, v[140:141]
	v_lshlrev_b64 v[142:143], v187, v[142:143]
	v_lshlrev_b64 v[136:137], v188, v[136:137]
	v_lshlrev_b64 v[138:139], v189, v[138:139]
	v_lshlrev_b64 v[112:113], v190, v[112:113]
	v_lshlrev_b64 v[114:115], v191, v[114:115]
	v_lshlrev_b64 v[80:81], v192, v[80:81]
	v_lshlrev_b64 v[82:83], v193, v[82:83]
	v_min_u32_e32 v140, 1, v140
	v_min_u32_e32 v142, 1, v142
	v_min_u32_e32 v136, 1, v136
	v_min_u32_e32 v138, 1, v138
	v_min_u32_e32 v112, 1, v112
	v_min_u32_e32 v114, 1, v114
	v_min_u32_e32 v80, 1, v80
	v_min_u32_e32 v82, 1, v82
	v_or_b32_e32 v140, v141, v140
	v_or_b32_e32 v142, v143, v142
	v_or_b32_e32 v136, v137, v136
	v_or_b32_e32 v138, v139, v138
	v_or_b32_e32 v112, v113, v112
	v_or_b32_e32 v114, v115, v114
	v_or_b32_e32 v80, v81, v80
	v_or_b32_e32 v82, v83, v82
	v_cvt_f32_u32_e32 v140, v140
	v_cvt_f32_u32_e32 v142, v142
	v_cvt_f32_u32_e32 v136, v136
	v_cvt_f32_u32_e32 v138, v138
	v_cvt_f32_u32_e32 v112, v112
	v_cvt_f32_u32_e32 v114, v114
	v_cvt_f32_u32_e32 v80, v80
	v_cvt_f32_u32_e32 v82, v82
	v_sub_u32_e32 v186, 32, v186
	v_sub_u32_e32 v187, 32, v187
	v_sub_u32_e32 v188, 32, v188
	v_sub_u32_e32 v189, 32, v189
	v_sub_u32_e32 v190, 32, v190
	v_sub_u32_e32 v191, 32, v191
	v_sub_u32_e32 v192, 32, v192
	v_sub_u32_e32 v193, 32, v193
	v_ldexp_f32 v140, v140, v186
	v_ldexp_f32 v142, v142, v187
	v_ldexp_f32 v136, v136, v188
	v_ldexp_f32 v138, v138, v189
	v_ldexp_f32 v112, v112, v190
	v_ldexp_f32 v114, v114, v191
	v_ldexp_f32 v80, v80, v192
	v_ldexp_f32 v82, v82, v193
	v_mul_f32_e32 v140, 0x35800000, v140
	v_mul_f32_e32 v142, 0x35800000, v142
	v_mul_f32_e32 v136, 0x35800000, v136
	v_mul_f32_e32 v138, 0x35800000, v138
	v_mul_f32_e32 v112, 0x35800000, v112
	v_mul_f32_e32 v114, 0x35800000, v114
	v_mul_f32_e32 v80, 0x35800000, v80
	v_mul_f32_e32 v82, 0x35800000, v82
	v_fmamk_f32 v140, v140, 0x3a800000, v165
	v_fmamk_f32 v142, v142, 0x3a800000, v165
	v_fmamk_f32 v136, v136, 0x3a800000, v165
	v_fmamk_f32 v138, v138, 0x3a800000, v165
	v_fmamk_f32 v112, v112, 0x3a800000, v165
	v_fmamk_f32 v114, v114, 0x3a800000, v165
	v_fmamk_f32 v80, v80, 0x3a800000, v165
	v_fmamk_f32 v82, v82, 0x3a800000, v165
	v_rsq_f32_e32 v232, v140
	v_rsq_f32_e32 v234, v142
	v_rsq_f32_e32 v236, v136
	v_rsq_f32_e32 v238, v138
	v_rsq_f32_e32 v240, v112
	v_rsq_f32_e32 v242, v114
	v_rsq_f32_e32 v244, v80
	v_rsq_f32_e32 v246, v82
	s_nop 0
	v_mul_f32_e32 v232, s82, v232
	v_mul_f32_e32 v234, s82, v234
	v_mul_f32_e32 v236, s82, v236
	v_mul_f32_e32 v238, s82, v238
	v_mul_f32_e32 v240, s82, v240
	v_mul_f32_e32 v242, s82, v242
	v_mul_f32_e32 v244, s82, v244
	v_mul_f32_e32 v246, s82, v246
	v_pk_mul_f32 v[170:171], v[132:133], v[232:233] op_sel_hi:[1,0]
	v_pk_mul_f32 v[172:173], v[134:135], v[232:233] op_sel_hi:[1,0]
	v_pk_mul_f32 v[174:175], v[124:125], v[232:233] op_sel_hi:[1,0]
	v_pk_mul_f32 v[176:177], v[126:127], v[232:233] op_sel_hi:[1,0]
	v_exp_f32_e32 v170, v170
	v_exp_f32_e32 v171, v171
	v_exp_f32_e32 v172, v172
	v_exp_f32_e32 v173, v173
	v_exp_f32_e32 v174, v174
	v_exp_f32_e32 v175, v175
	v_exp_f32_e32 v176, v176
	v_exp_f32_e32 v177, v177
	v_pk_fma_f32 v[170:171], v[170:171], v[140:141], v[140:141] op_sel_hi:[1,0,0]
	v_pk_fma_f32 v[172:173], v[172:173], v[140:141], v[140:141] op_sel_hi:[1,0,0]
	v_pk_fma_f32 v[174:175], v[174:175], v[140:141], v[140:141] op_sel_hi:[1,0,0]
	v_pk_fma_f32 v[176:177], v[176:177], v[140:141], v[140:141] op_sel_hi:[1,0,0]
	v_rcp_f32_e32 v170, v170
	v_rcp_f32_e32 v171, v171
	v_rcp_f32_e32 v172, v172
	v_rcp_f32_e32 v173, v173
	v_rcp_f32_e32 v174, v174
	v_rcp_f32_e32 v175, v175
	v_rcp_f32_e32 v176, v176
	v_rcp_f32_e32 v177, v177
	v_pk_mul_f32 v[170:171], v[132:133], v[170:171]
	v_pk_mul_f32 v[172:173], v[134:135], v[172:173]
	v_pk_mul_f32 v[174:175], v[124:125], v[174:175]
	v_pk_mul_f32 v[176:177], v[126:127], v[176:177]
	v_pk_mul_f32 v[170:171], v[128:129], v[170:171]
	v_pk_mul_f32 v[172:173], v[130:131], v[172:173]
	v_pk_mul_f32 v[174:175], v[120:121], v[174:175]
	v_pk_mul_f32 v[176:177], v[122:123], v[176:177]
	v_cvt_pk_bf16_f32 v194, v170, v171
	v_cvt_pk_bf16_f32 v195, v172, v173
	v_cvt_pk_bf16_f32 v196, v174, v175
	v_cvt_pk_bf16_f32 v197, v176, v177
	global_store_dwordx4 v[156:157], v[194:197], off
	v_lshl_add_u64 v[156:157], v[156:157], 0, s[20:21]
	v_pk_mul_f32 v[178:179], v[116:117], v[234:235] op_sel_hi:[1,0]
	v_pk_mul_f32 v[180:181], v[118:119], v[234:235] op_sel_hi:[1,0]
	v_pk_mul_f32 v[182:183], v[104:105], v[234:235] op_sel_hi:[1,0]
	v_pk_mul_f32 v[184:185], v[106:107], v[234:235] op_sel_hi:[1,0]
	v_exp_f32_e32 v178, v178
	v_exp_f32_e32 v179, v179
	v_exp_f32_e32 v180, v180
	v_exp_f32_e32 v181, v181
	v_exp_f32_e32 v182, v182
	v_exp_f32_e32 v183, v183
	v_exp_f32_e32 v184, v184
	v_exp_f32_e32 v185, v185
	v_pk_fma_f32 v[178:179], v[178:179], v[142:143], v[142:143] op_sel_hi:[1,0,0]
	v_pk_fma_f32 v[180:181], v[180:181], v[142:143], v[142:143] op_sel_hi:[1,0,0]
	v_pk_fma_f32 v[182:183], v[182:183], v[142:143], v[142:143] op_sel_hi:[1,0,0]
	v_pk_fma_f32 v[184:185], v[184:185], v[142:143], v[142:143] op_sel_hi:[1,0,0]
	v_rcp_f32_e32 v178, v178
	v_rcp_f32_e32 v179, v179
	v_rcp_f32_e32 v180, v180
	v_rcp_f32_e32 v181, v181
	v_rcp_f32_e32 v182, v182
	v_rcp_f32_e32 v183, v183
	v_rcp_f32_e32 v184, v184
	v_rcp_f32_e32 v185, v185
	v_pk_mul_f32 v[178:179], v[116:117], v[178:179]
	v_pk_mul_f32 v[180:181], v[118:119], v[180:181]
	v_pk_mul_f32 v[182:183], v[104:105], v[182:183]
	v_pk_mul_f32 v[184:185], v[106:107], v[184:185]
	v_pk_mul_f32 v[178:179], v[108:109], v[178:179]
	v_pk_mul_f32 v[180:181], v[110:111], v[180:181]
	v_pk_mul_f32 v[182:183], v[100:101], v[182:183]
	v_pk_mul_f32 v[184:185], v[102:103], v[184:185]
	v_cvt_pk_bf16_f32 v198, v178, v179
	v_cvt_pk_bf16_f32 v199, v180, v181
	v_cvt_pk_bf16_f32 v200, v182, v183
	v_cvt_pk_bf16_f32 v201, v184, v185
	global_store_dwordx4 v[156:157], v[198:201], off
	v_lshl_add_u64 v[156:157], v[156:157], 0, s[20:21]
	v_pk_mul_f32 v[170:171], v[96:97], v[236:237] op_sel_hi:[1,0]
	v_pk_mul_f32 v[172:173], v[98:99], v[236:237] op_sel_hi:[1,0]
	v_pk_mul_f32 v[174:175], v[88:89], v[236:237] op_sel_hi:[1,0]
	v_pk_mul_f32 v[176:177], v[90:91], v[236:237] op_sel_hi:[1,0]
	v_exp_f32_e32 v170, v170
	v_exp_f32_e32 v171, v171
	v_exp_f32_e32 v172, v172
	v_exp_f32_e32 v173, v173
	v_exp_f32_e32 v174, v174
	v_exp_f32_e32 v175, v175
	v_exp_f32_e32 v176, v176
	v_exp_f32_e32 v177, v177
	v_pk_fma_f32 v[170:171], v[170:171], v[136:137], v[136:137] op_sel_hi:[1,0,0]
	v_pk_fma_f32 v[172:173], v[172:173], v[136:137], v[136:137] op_sel_hi:[1,0,0]
	v_pk_fma_f32 v[174:175], v[174:175], v[136:137], v[136:137] op_sel_hi:[1,0,0]
	v_pk_fma_f32 v[176:177], v[176:177], v[136:137], v[136:137] op_sel_hi:[1,0,0]
	v_rcp_f32_e32 v170, v170
	v_rcp_f32_e32 v171, v171
	v_rcp_f32_e32 v172, v172
	v_rcp_f32_e32 v173, v173
	v_rcp_f32_e32 v174, v174
	v_rcp_f32_e32 v175, v175
	v_rcp_f32_e32 v176, v176
	v_rcp_f32_e32 v177, v177
	v_pk_mul_f32 v[170:171], v[96:97], v[170:171]
	v_pk_mul_f32 v[172:173], v[98:99], v[172:173]
	v_pk_mul_f32 v[174:175], v[88:89], v[174:175]
	v_pk_mul_f32 v[176:177], v[90:91], v[176:177]
	v_pk_mul_f32 v[170:171], v[92:93], v[170:171]
	v_pk_mul_f32 v[172:173], v[94:95], v[172:173]
	v_pk_mul_f32 v[174:175], v[84:85], v[174:175]
	v_pk_mul_f32 v[176:177], v[86:87], v[176:177]
	v_cvt_pk_bf16_f32 v194, v170, v171
	v_cvt_pk_bf16_f32 v195, v172, v173
	v_cvt_pk_bf16_f32 v196, v174, v175
	v_cvt_pk_bf16_f32 v197, v176, v177
	global_store_dwordx4 v[156:157], v[194:197], off
	v_lshl_add_u64 v[156:157], v[156:157], 0, s[20:21]
	v_pk_mul_f32 v[178:179], v[76:77], v[238:239] op_sel_hi:[1,0]
	v_pk_mul_f32 v[180:181], v[78:79], v[238:239] op_sel_hi:[1,0]
	v_pk_mul_f32 v[182:183], v[68:69], v[238:239] op_sel_hi:[1,0]
	v_pk_mul_f32 v[184:185], v[70:71], v[238:239] op_sel_hi:[1,0]
	v_exp_f32_e32 v178, v178
	v_exp_f32_e32 v179, v179
	v_exp_f32_e32 v180, v180
	v_exp_f32_e32 v181, v181
	v_exp_f32_e32 v182, v182
	v_exp_f32_e32 v183, v183
	v_exp_f32_e32 v184, v184
	v_exp_f32_e32 v185, v185
	v_pk_fma_f32 v[178:179], v[178:179], v[138:139], v[138:139] op_sel_hi:[1,0,0]
	v_pk_fma_f32 v[180:181], v[180:181], v[138:139], v[138:139] op_sel_hi:[1,0,0]
	v_pk_fma_f32 v[182:183], v[182:183], v[138:139], v[138:139] op_sel_hi:[1,0,0]
	v_pk_fma_f32 v[184:185], v[184:185], v[138:139], v[138:139] op_sel_hi:[1,0,0]
	v_rcp_f32_e32 v178, v178
	v_rcp_f32_e32 v179, v179
	v_rcp_f32_e32 v180, v180
	v_rcp_f32_e32 v181, v181
	v_rcp_f32_e32 v182, v182
	v_rcp_f32_e32 v183, v183
	v_rcp_f32_e32 v184, v184
	v_rcp_f32_e32 v185, v185
	v_pk_mul_f32 v[178:179], v[76:77], v[178:179]
	v_pk_mul_f32 v[180:181], v[78:79], v[180:181]
	v_pk_mul_f32 v[182:183], v[68:69], v[182:183]
	v_pk_mul_f32 v[184:185], v[70:71], v[184:185]
	v_pk_mul_f32 v[178:179], v[72:73], v[178:179]
	v_pk_mul_f32 v[180:181], v[74:75], v[180:181]
	v_pk_mul_f32 v[182:183], v[64:65], v[182:183]
	v_pk_mul_f32 v[184:185], v[66:67], v[184:185]
	v_cvt_pk_bf16_f32 v198, v178, v179
	v_cvt_pk_bf16_f32 v199, v180, v181
	v_cvt_pk_bf16_f32 v200, v182, v183
	v_cvt_pk_bf16_f32 v201, v184, v185
	global_store_dwordx4 v[156:157], v[198:201], off
	v_lshl_add_u64 v[156:157], v[156:157], 0, s[30:31]
	v_pk_mul_f32 v[170:171], v[60:61], v[240:241] op_sel_hi:[1,0]
	v_pk_mul_f32 v[172:173], v[62:63], v[240:241] op_sel_hi:[1,0]
	v_pk_mul_f32 v[174:175], v[52:53], v[240:241] op_sel_hi:[1,0]
	v_pk_mul_f32 v[176:177], v[54:55], v[240:241] op_sel_hi:[1,0]
	v_exp_f32_e32 v170, v170
	v_exp_f32_e32 v171, v171
	v_exp_f32_e32 v172, v172
	v_exp_f32_e32 v173, v173
	v_exp_f32_e32 v174, v174
	v_exp_f32_e32 v175, v175
	v_exp_f32_e32 v176, v176
	v_exp_f32_e32 v177, v177
	v_pk_fma_f32 v[170:171], v[170:171], v[112:113], v[112:113] op_sel_hi:[1,0,0]
	v_pk_fma_f32 v[172:173], v[172:173], v[112:113], v[112:113] op_sel_hi:[1,0,0]
	v_pk_fma_f32 v[174:175], v[174:175], v[112:113], v[112:113] op_sel_hi:[1,0,0]
	v_pk_fma_f32 v[176:177], v[176:177], v[112:113], v[112:113] op_sel_hi:[1,0,0]
	v_rcp_f32_e32 v170, v170
	v_rcp_f32_e32 v171, v171
	v_rcp_f32_e32 v172, v172
	v_rcp_f32_e32 v173, v173
	v_rcp_f32_e32 v174, v174
	v_rcp_f32_e32 v175, v175
	v_rcp_f32_e32 v176, v176
	v_rcp_f32_e32 v177, v177
	v_pk_mul_f32 v[170:171], v[60:61], v[170:171]
	v_pk_mul_f32 v[172:173], v[62:63], v[172:173]
	v_pk_mul_f32 v[174:175], v[52:53], v[174:175]
	v_pk_mul_f32 v[176:177], v[54:55], v[176:177]
	v_pk_mul_f32 v[170:171], v[56:57], v[170:171]
	v_pk_mul_f32 v[172:173], v[58:59], v[172:173]
	v_pk_mul_f32 v[174:175], v[48:49], v[174:175]
	v_pk_mul_f32 v[176:177], v[50:51], v[176:177]
	v_cvt_pk_bf16_f32 v194, v170, v171
	v_cvt_pk_bf16_f32 v195, v172, v173
	v_cvt_pk_bf16_f32 v196, v174, v175
	v_cvt_pk_bf16_f32 v197, v176, v177
	global_store_dwordx4 v[156:157], v[194:197], off
	v_lshl_add_u64 v[156:157], v[156:157], 0, s[20:21]
	v_pk_mul_f32 v[178:179], v[44:45], v[242:243] op_sel_hi:[1,0]
	v_pk_mul_f32 v[180:181], v[46:47], v[242:243] op_sel_hi:[1,0]
	v_pk_mul_f32 v[182:183], v[36:37], v[242:243] op_sel_hi:[1,0]
	v_pk_mul_f32 v[184:185], v[38:39], v[242:243] op_sel_hi:[1,0]
	v_exp_f32_e32 v178, v178
	v_exp_f32_e32 v179, v179
	v_exp_f32_e32 v180, v180
	v_exp_f32_e32 v181, v181
	v_exp_f32_e32 v182, v182
	v_exp_f32_e32 v183, v183
	v_exp_f32_e32 v184, v184
	v_exp_f32_e32 v185, v185
	v_pk_fma_f32 v[178:179], v[178:179], v[114:115], v[114:115] op_sel_hi:[1,0,0]
	v_pk_fma_f32 v[180:181], v[180:181], v[114:115], v[114:115] op_sel_hi:[1,0,0]
	v_pk_fma_f32 v[182:183], v[182:183], v[114:115], v[114:115] op_sel_hi:[1,0,0]
	v_pk_fma_f32 v[184:185], v[184:185], v[114:115], v[114:115] op_sel_hi:[1,0,0]
	v_rcp_f32_e32 v178, v178
	v_rcp_f32_e32 v179, v179
	v_rcp_f32_e32 v180, v180
	v_rcp_f32_e32 v181, v181
	v_rcp_f32_e32 v182, v182
	v_rcp_f32_e32 v183, v183
	v_rcp_f32_e32 v184, v184
	v_rcp_f32_e32 v185, v185
	v_pk_mul_f32 v[178:179], v[44:45], v[178:179]
	v_pk_mul_f32 v[180:181], v[46:47], v[180:181]
	v_pk_mul_f32 v[182:183], v[36:37], v[182:183]
	v_pk_mul_f32 v[184:185], v[38:39], v[184:185]
	v_pk_mul_f32 v[178:179], v[40:41], v[178:179]
	v_pk_mul_f32 v[180:181], v[42:43], v[180:181]
	v_pk_mul_f32 v[182:183], v[32:33], v[182:183]
	v_pk_mul_f32 v[184:185], v[34:35], v[184:185]
	v_cvt_pk_bf16_f32 v198, v178, v179
	v_cvt_pk_bf16_f32 v199, v180, v181
	v_cvt_pk_bf16_f32 v200, v182, v183
	v_cvt_pk_bf16_f32 v201, v184, v185
	global_store_dwordx4 v[156:157], v[198:201], off
	v_lshl_add_u64 v[156:157], v[156:157], 0, s[20:21]
	v_pk_mul_f32 v[170:171], v[28:29], v[244:245] op_sel_hi:[1,0]
	v_pk_mul_f32 v[172:173], v[30:31], v[244:245] op_sel_hi:[1,0]
	v_pk_mul_f32 v[174:175], v[20:21], v[244:245] op_sel_hi:[1,0]
	v_pk_mul_f32 v[176:177], v[22:23], v[244:245] op_sel_hi:[1,0]
	v_exp_f32_e32 v170, v170
	v_exp_f32_e32 v171, v171
	v_exp_f32_e32 v172, v172
	v_exp_f32_e32 v173, v173
	v_exp_f32_e32 v174, v174
	v_exp_f32_e32 v175, v175
	v_exp_f32_e32 v176, v176
	v_exp_f32_e32 v177, v177
	v_pk_fma_f32 v[170:171], v[170:171], v[80:81], v[80:81] op_sel_hi:[1,0,0]
	v_pk_fma_f32 v[172:173], v[172:173], v[80:81], v[80:81] op_sel_hi:[1,0,0]
	v_pk_fma_f32 v[174:175], v[174:175], v[80:81], v[80:81] op_sel_hi:[1,0,0]
	v_pk_fma_f32 v[176:177], v[176:177], v[80:81], v[80:81] op_sel_hi:[1,0,0]
	v_rcp_f32_e32 v170, v170
	v_rcp_f32_e32 v171, v171
	v_rcp_f32_e32 v172, v172
	v_rcp_f32_e32 v173, v173
	v_rcp_f32_e32 v174, v174
	v_rcp_f32_e32 v175, v175
	v_rcp_f32_e32 v176, v176
	v_rcp_f32_e32 v177, v177
	v_pk_mul_f32 v[170:171], v[28:29], v[170:171]
	v_pk_mul_f32 v[172:173], v[30:31], v[172:173]
	v_pk_mul_f32 v[174:175], v[20:21], v[174:175]
	v_pk_mul_f32 v[176:177], v[22:23], v[176:177]
	v_pk_mul_f32 v[170:171], v[24:25], v[170:171]
	v_pk_mul_f32 v[172:173], v[26:27], v[172:173]
	v_pk_mul_f32 v[174:175], v[16:17], v[174:175]
	v_pk_mul_f32 v[176:177], v[18:19], v[176:177]
	v_cvt_pk_bf16_f32 v194, v170, v171
	v_cvt_pk_bf16_f32 v195, v172, v173
	v_cvt_pk_bf16_f32 v196, v174, v175
	v_cvt_pk_bf16_f32 v197, v176, v177
	global_store_dwordx4 v[156:157], v[194:197], off
	v_lshl_add_u64 v[156:157], v[156:157], 0, s[20:21]
	v_pk_mul_f32 v[178:179], v[12:13], v[246:247] op_sel_hi:[1,0]
	v_pk_mul_f32 v[180:181], v[14:15], v[246:247] op_sel_hi:[1,0]
	v_pk_mul_f32 v[182:183], v[4:5], v[246:247] op_sel_hi:[1,0]
	v_pk_mul_f32 v[184:185], v[6:7], v[246:247] op_sel_hi:[1,0]
	v_exp_f32_e32 v178, v178
	v_exp_f32_e32 v179, v179
	v_exp_f32_e32 v180, v180
	v_exp_f32_e32 v181, v181
	v_exp_f32_e32 v182, v182
	v_exp_f32_e32 v183, v183
	v_exp_f32_e32 v184, v184
	v_exp_f32_e32 v185, v185
	v_pk_fma_f32 v[178:179], v[178:179], v[82:83], v[82:83] op_sel_hi:[1,0,0]
	v_pk_fma_f32 v[180:181], v[180:181], v[82:83], v[82:83] op_sel_hi:[1,0,0]
	v_pk_fma_f32 v[182:183], v[182:183], v[82:83], v[82:83] op_sel_hi:[1,0,0]
	v_pk_fma_f32 v[184:185], v[184:185], v[82:83], v[82:83] op_sel_hi:[1,0,0]
	v_rcp_f32_e32 v178, v178
	v_rcp_f32_e32 v179, v179
	v_rcp_f32_e32 v180, v180
	v_rcp_f32_e32 v181, v181
	v_rcp_f32_e32 v182, v182
	v_rcp_f32_e32 v183, v183
	v_rcp_f32_e32 v184, v184
	v_rcp_f32_e32 v185, v185
	v_pk_mul_f32 v[178:179], v[12:13], v[178:179]
	v_pk_mul_f32 v[180:181], v[14:15], v[180:181]
	v_pk_mul_f32 v[182:183], v[4:5], v[182:183]
	v_pk_mul_f32 v[184:185], v[6:7], v[184:185]
	v_pk_mul_f32 v[178:179], v[8:9], v[178:179]
	v_pk_mul_f32 v[180:181], v[10:11], v[180:181]
	v_pk_mul_f32 v[182:183], v[0:1], v[182:183]
	v_pk_mul_f32 v[184:185], v[2:3], v[184:185]
	v_cvt_pk_bf16_f32 v198, v178, v179
	v_cvt_pk_bf16_f32 v199, v180, v181
	v_cvt_pk_bf16_f32 v200, v182, v183
	v_cvt_pk_bf16_f32 v201, v184, v185
	global_store_dwordx4 v[156:157], v[198:201], off
	s_and_b64 vcc, exec, s[8:9]
	s_cbranch_vccz .LBB0_666
	s_lshl_b32 s8, s16, 8
	s_lshl_b32 s3, s94, 11
	s_ashr_i32 s9, s8, 31
	s_and_b32 s3, s3, 0x800
	v_lshl_add_u64 v[0:1], s[8:9], 3, v[150:151]
	s_add_i32 m0, s46, s3
	s_nop 0
	global_load_lds_dwordx4 v[0:1], off
	s_branch .LBB0_666
	s_nop 0
	s_nop 0
	s_nop 0
	s_nop 0
	s_nop 0
	s_nop 0
	s_nop 0
	s_nop 0
	s_nop 0
	s_nop 0
	s_nop 0
	s_nop 0
	s_nop 0
	s_nop 0
	s_nop 0
	s_nop 0
	s_nop 0
	s_nop 0
	s_nop 0
	s_nop 0
	s_nop 0
